# attention head-per-workgroup map now also requires the task stride to be a multiple of 64 (same behaviour at 256 workgroups); per-task barrier kept
# speedup vs baseline: 1.0265x; 1.0054x over previous
; #define LAS __attribute__((address_space(3)))
; __device__ __forceinline__ int tid_() { int t = threadIdx.x; asm volatile("" : "+v"(t)); return t; }
; __device__ __forceinline__ int bid_() { int t = blockIdx.x; asm volatile("" : "+s"(t)); return t; }
; __device__ __forceinline__ int nblk_() { int t = gridDim.x; asm volatile("" : "+s"(t)); return t; }
; __device__ __forceinline__ void attn_all(KArgs& a, LAS unsigned char* lds, int l) {
;     const int tid = tid_(), lane = tid & 63, wave = __builtin_amdgcn_readfirstlane(tid >> 6), q32 = lane & 31, g = lane >> 5;
;     LAS float* rpb_s = (LAS float*)(lds + 1024);
;     for (int i = tid; i < 3720; i += 512) rpb_s[i] = a.na_rpb[l * 3720 + i] * 1.44269504f;
;     LAS unsigned char* wbuf = lds + 16384 + wave * 16384;
;     __syncthreads();
;     const bf16_t* PA = (const bf16_t*)(a.ws + OFF_R1); const bf16_t* VT = (const bf16_t*)(a.ws + OFF_VT); const bf16_t* KH = (const bf16_t*)(a.ws + OFF_KH); bf16_t* OA = (bf16_t*)(a.ws + OFF_R2 + 2 * SZ_ACT);
;     const int nb = nblk_(), bid = nb - 1 - bid_(), ntb = 1024 + (l < DEPTH - 1 ? 64 : 0);
;     const bool xl = (nb & 7) == 0;
;     const int gw = xl ? (bid >> 3) * 8 + wave : bid * 8 + wave, ngw = xl ? nb : nb * 8, tend = xl ? ntb : 8 * ntb;
;     for (int ti = gw; ti < tend; ti += ngw) {
;         const int b = xl ? (bid & 7) : ti / ntb, task = xl ? ti : ti - b * ntb;
;         int h, qtok, n_local = 0, krow_lo = 0, tc0 = 0, qrow_g = 0, qcol = 0, r0q = 0;
.LBB0_490:
	s_or_b64 exec, exec, s[0:1]
	s_waitcnt lgkmcnt(0)
	v_readlane_b32 s4, v237, 2
	v_readlane_b32 s5, v237, 3
	s_waitcnt vmcnt(0)
	s_barrier
	s_load_dwordx2 s[0:1], s[4:5], 0xf0
	s_waitcnt lgkmcnt(0)
	s_mov_b32 s1, s84
	s_not_b32 s1, s1
	s_ashr_i32 s8, s6, 6
	s_add_i32 s3, s0, s1
	s_cmp_lt_i32 s2, 3
	s_cselect_b32 s2, s95, 0x400
	s_and_b32 s9, s0, 7
	s_cmp_lg_u32 s9, 0
	s_cselect_b64 s[4:5], -1, 0
	s_and_b32 s22, s3, -8
	s_lshl_b32 s3, s3, 3
	s_lshl_b32 s23, s2, 3
	s_cmp_eq_u32 s9, 0
	s_cselect_b64 s[16:17], -1, 0
	s_and_b64 s[18:19], s[16:17], exec
	s_cselect_b32 s9, s22, s3
	s_cselect_b32 s3, s2, s23
	s_add_i32 s18, s9, s8
	s_cmp_ge_i32 s18, s3
	s_cbranch_scc1 .LBB0_524
	s_lshl_b32 s8, s8, 14
	s_add_i32 s19, s8, 0
	s_add_u32 s24, s14, 0x174f8000
	v_and_b32_e32 v5, 31, v2
	v_bfe_u32 v6, v2, 5, 1
	v_and_b32_e32 v7, 7, v2
	v_bfe_u32 v8, v2, 3, 2
	s_addc_u32 s25, s15, 0
	v_lshlrev_b32_e32 v152, 10, v8
	v_bfe_u32 v8, v5, 3, 1
	v_lshlrev_b32_e32 v153, 7, v7
	v_bitop3_b32 v7, v6, v2, 7 bitop3:0x78
	s_add_u32 s31, s14, 0x152f8000
	v_xor_b32_e32 v7, v7, v8
	s_addc_u32 s33, s15, 0
	s_lshl_b32 s22, s0, 3
	v_lshlrev_b32_e32 v154, 4, v7
	v_or_b32_e32 v7, 2, v6
	s_and_b64 s[8:9], s[16:17], exec
	v_bitop3_b32 v7, v2, v7, 7 bitop3:0x6c
	s_cselect_b32 s34, s0, s22
	v_xor_b32_e32 v7, v7, v8
	s_bfe_u32 s36, s6, 0x30006
	s_bfe_u32 s100, s18, 0x30003
	s_and_b32 s101, s34, 63
	s_cselect_b32 s100, s36, s100
	s_cmp_lg_u64 s[16:17], 0
	s_cselect_b32 s36, s100, s36
	s_and_b32 s35, s1, 7
	v_lshlrev_b32_e32 v150, 2, v6
	v_lshlrev_b32_e32 v0, 3, v6
	v_bfe_u32 v151, v2, 3, 3
	v_lshlrev_b32_e32 v155, 4, v7
	v_or_b32_e32 v7, 4, v6
	v_or_b32_e32 v6, 6, v6
	s_lshl_b32 s6, s36, 6
	s_lshl_b32 s0, s36, 7
	v_and_b32_e32 v3, 63, v2
	v_bfe_u32 v148, v2, 4, 1
	v_and_b32_e32 v149, 15, v2
	v_bitop3_b32 v4, v151, v2, 7 bitop3:0x78
	v_bitop3_b32 v7, v2, v7, 7 bitop3:0x6c
	v_bitop3_b32 v2, v2, v6, 7 bitop3:0x6c
	s_add_u32 s0, s14, s0
	v_xor_b32_e32 v2, v2, v8
	s_addc_u32 s1, s15, 0
	v_lshlrev_b32_e32 v102, 4, v3
	v_lshlrev_b32_e32 v157, 4, v2
	v_cmp_gt_u32_e64 s[40:41], 32, v3
	v_lshl_add_u64 v[2:3], s[0:1], 0, v[0:1]
	s_mov_b64 s[0:1], 0x1daf8000
	v_lshl_add_u64 v[104:105], v[2:3], 0, s[0:1]
	v_cvt_f32_u32_e32 v2, s2
	s_sub_i32 s0, 0, s2
	v_lshlrev_b32_e32 v100, 3, v4
	s_mul_i32 s8, s36, 0x744
	v_rcp_iflag_f32_e32 v2, v2
	v_xor_b32_e32 v4, 8, v100
	v_xor_b32_e32 v7, v7, v8
	s_add_i32 s38, s8, 0
	v_mul_f32_e32 v2, 0x4f7ffffe, v2
	v_cvt_u32_f32_e32 v2, v2
	v_or_b32_e32 v101, 0xfffff000, v5
	v_mov_b32_e32 v103, v1
	v_lshlrev_b32_e32 v156, 4, v7
	v_readfirstlane_b32 s1, v2
	s_mul_i32 s0, s0, s1
	s_mul_hi_u32 s0, s1, s0
	v_lshlrev_b32_e32 v158, 4, v5
	s_add_i32 s37, s1, s0
	s_addk_i32 s38, 0x43c
	s_lshl_b32 s6, s6, 1
	v_lshlrev_b32_e32 v106, 1, v0
	v_lshlrev_b32_e32 v108, 1, v4
	s_add_i32 s39, s19, 0x4400
	s_add_i32 s42, s19, 0x4800
	s_add_i32 s43, s19, 0x4c00
	s_add_i32 s44, s19, 0x5000
	s_add_i32 s45, s19, 0x5400
	s_add_i32 s46, s19, 0x5800
	s_add_i32 s47, s19, 0x5c00
	s_add_i32 s48, s19, 0x6400
	s_add_i32 s49, s19, 0x6800
	s_add_i32 s52, s19, 0x6c00
	s_add_i32 s53, s19, 0x7000
	s_add_i32 s54, s19, 0x7400
	s_add_i32 s55, s19, 0x7800
	s_add_i32 s56, s19, 0x7c00
	s_branch .LBB0_493

; __device__ __forceinline__ void attn_all(KArgs& a, LAS unsigned char* lds, int l) {
;     ...
;         const int b = xl ? (bid & 7) : ti / ntb, task = xl ? ti : ti - b * ntb;
;         int h, qtok, n_local = 0, krow_lo = 0, tc0 = 0, qrow_g = 0, qcol = 0, r0q = 0;
;         float cadd[16];
; #pragma unroll
;         for (int j = 0; j < 16; ++j) cadd[j] = 0.f;
;         if (task < 1024) {
;             h = task & 7; const int cb = (task >> 3) & 3, rp = task >> 5;
;             const int rr0 = 2 * rp; qrow_g = rr0 + (q32 >> 4); qcol = cb * 16 + (q32 & 15);
;             qtok = b * TPB + CTXL + qrow_g * 64 + qcol;
;             r0q = min(max(qrow_g - 4, 0), 56); const int csq = min(max(qcol - 8, 0), 48);
;             tc0 = min(max(cb * 16 - 8, 0), 32);
;             krow_lo = min(max(rr0 - 4, 0), 56); n_local = min(max(rr0 - 3, 0), 56) + 8 - krow_lo;
; #pragma unroll
;             for (int j = 0; j < 16; ++j) { const int ko = 8 * (j >> 2) + 4 * g + (j & 3); cadd[j] = (unsigned)(tc0 + ko - csq) < 16u ? 0.f : -1e30f; }
;         } else { const int j = task - 1024; h = j & 7; qtok = b * TPB + (j >> 3) * 32 + q32; }
.LBB0_495:
	s_mul_i32 s9, s8, s2
	s_and_b64 s[0:1], s[16:17], exec
	s_cselect_b32 s0, 0, s9
	s_sub_i32 s22, s18, s0
	s_lshr_b32 s100, s19, 11
	s_andn2_b32 s101, s22, 56
	s_or_b32 s101, s101, s100
	s_and_b32 s100, s34, 63
	s_cselect_b32 s101, s22, s101
	s_cmp_lg_u64 s[16:17], 0
	s_cselect_b32 s101, s101, s22
	s_mov_b64 s[0:1], -1
	s_cmpk_gt_i32 s22, 0x3ff
	s_mul_i32 s9, s8, 0x1100
	s_cbranch_scc0 .LBB0_497
	s_lshl_b32 s0, s101, 2
	s_andn2_b32 s0, s0, 31
	s_add_i32 s0, s0, s9
	v_add_u32_e32 v110, s0, v101
	s_mov_b64 s[0:1], 0
